# v88 + conversion sets rebalanced: ph9 converts ids 13,17,16,7,6; ph11 converts ids 19,10
# baseline (speedup 1.0000x reference)
.LBB0_31:
	s_andn2_b64 vcc, exec, s[2:3]
	v_readlane_b32 s2, v209, 28
	v_readlane_b32 s76, v209, 22
	v_readlane_b32 s26, v209, 24
	v_readlane_b32 s3, v209, 29
	v_readlane_b32 s77, v209, 23
	v_readlane_b32 s27, v209, 25
	v_writelane_b32 v209, s2, 26
	s_nop 1
	v_writelane_b32 v209, s3, 27
	s_cbranch_vccnz .LBB0_403
	v_readlane_b32 s3, v209, 42
	s_add_i32 s0, s3, -1
	s_mul_hi_i32 s1, s0, 0x66666667
	s_lshr_b32 s2, s1, 31
	s_ashr_i32 s1, s1, 1
	s_add_i32 s84, s1, s2
	s_ashr_i32 s85, s84, 31
	s_mul_i32 s2, s84, 0x1600000
	v_readlane_b32 s4, v209, 38
	s_mul_hi_i32 s1, s84, 0x1600000
	v_readlane_b32 s5, v209, 39
	s_add_u32 s4, s4, s2
	s_addc_u32 s5, s5, s1
	v_writelane_b32 v209, s4, 43
	s_mul_i32 s1, s84, 5
	s_mov_b64 s[6:7], -1
	v_writelane_b32 v209, s5, 44
	s_sub_i32 s4, s0, s1
	s_add_u32 s16, s18, 0x15e00000
	s_addc_u32 s17, s19, 0
	s_add_u32 s82, s18, 0x19e00000
	s_addc_u32 s83, s19, 0
	s_add_u32 s34, s18, 0x1be00000
	s_addc_u32 s35, s19, 0
	s_add_u32 s0, s18, 0x1de00000
	s_addc_u32 s1, s19, 0
	s_add_i32 s2, s84, -2
	v_writelane_b32 v209, s0, 45
	s_cmp_gt_i32 s3, 10
	s_mov_b64 s[10:11], 0
	v_writelane_b32 v209, s1, 46
	s_cselect_b64 s[0:1], -1, 0
	v_writelane_b32 v209, s0, 47
	s_nop 1
	v_writelane_b32 v209, s1, 48
	s_mov_b32 s0, s2
	v_writelane_b32 v209, s0, 49
	s_nop 1
	v_writelane_b32 v209, s1, 50
	s_lshl_b32 s0, s2, 11
	s_ashr_i32 s1, s0, 31
	v_writelane_b32 v209, s0, 51
	s_mov_b64 s[2:3], 0
	s_cmp_lt_i32 s4, 2
	v_writelane_b32 v209, s1, 52
	v_writelane_b32 v209, s4, 53
	v_writelane_b32 v209, s2, 54
	s_nop 1
	v_writelane_b32 v209, s3, 55
	s_cbranch_scc1 .LBB0_128
	v_readlane_b32 s2, v209, 53
	s_mov_b64 s[0:1], -1
	s_mov_b64 s[8:9], 0
	s_cmp_gt_i32 s2, 2
	s_mov_b64 s[2:3], 0
	s_cbranch_scc0 .LBB0_124
	v_readlane_b32 s0, v209, 53
	s_cmp_eq_u32 s0, 3
	s_mov_b64 s[2:3], -1
	s_cbranch_scc0 .LBB0_123
	v_readlane_b32 s0, v253, 63
	v_readlane_b32 s1, v254, 0
	s_andn2_b64 vcc, exec, s[0:1]
	v_readlane_b32 s20, v254, 1
	s_cbranch_vccnz .LBB0_84
	v_readlane_b32 s2, v209, 42
	s_add_i32 s0, s2, 3
	s_add_i32 s1, s2, -6
	s_add_i32 s2, s2, -11
	s_cmp_lt_u32 s2, 5
	s_mov_b32 s2, 0x1f5d24e
	s_cselect_b32 s2, s2, 0x3ef
	s_cmp_gt_u32 s1, 4
	v_mov_b32_e32 v0, v234
	s_cselect_b32 s1, s2, 0x3e63c22d
	s_cmp_gt_u32 s0, 8
	s_cselect_b32 s26, s1, 0x3e548c2c
	v_readfirstlane_b32 s3, v0
	s_lshr_b32 s3, s3, 6
	v_lshlrev_b32_e32 v1, 2, v0
	s_mulk_i32 s3, 0x4100
	v_bfe_u32 v9, v0, 4, 2
	v_and_b32_e32 v8, 60, v1
	s_add_i32 s3, s3, 0
	v_lshlrev_b32_e32 v1, 2, v8
	v_mul_u32_u24_e32 v2, 0x104, v9
	v_add3_u32 v11, s3, v1, v2
	v_and_b32_e32 v1, 7, v0
	v_readlane_b32 s4, v209, 30
	v_lshlrev_b32_e32 v204, 4, v1
	v_readlane_b32 s5, v209, 31
	v_readfirstlane_b32 s0, v234
	v_bfe_u32 v78, v0, 3, 3
	v_lshl_add_u64 v[12:13], s[4:5], 0, v[204:205]
	v_readlane_b32 s4, v209, 38
	v_readlane_b32 s5, v209, 39
	s_mov_b32 s27, 0
	s_lshr_b32 s2, s0, 6
	v_lshl_add_u64 v[14:15], s[4:5], 0, v[204:205]
	v_readlane_b32 s4, v209, 32
	v_readlane_b32 s5, v209, 33
	v_readlane_b32 s0, v254, 4
	v_lshlrev_b32_e32 v10, 3, v1
	v_lshl_add_u64 v[16:17], s[4:5], 0, v[204:205]
	v_readlane_b32 s4, v209, 36
	v_readlane_b32 s5, v209, 37
	v_mul_u32_u24_e32 v0, 0x820, v1
	v_lshlrev_b32_e32 v1, 2, v78
	v_lshl_add_u64 v[20:21], s[4:5], 0, v[204:205]
	v_readlane_b32 s4, v209, 34
	v_readlane_b32 s5, v209, 35
	s_add_i32 s2, s2, s0
	s_and_b32 s0, s26, 15
	v_lshl_add_u64 v[22:23], s[4:5], 0, v[204:205]
	v_readlane_b32 s4, v209, 40
	v_readlane_b32 s5, v209, 41
	s_mov_b32 s1, s27
	v_add3_u32 v79, s3, v0, v1
	v_or_b32_e32 v80, 8, v78
	v_or_b32_e32 v81, 16, v78
	v_or_b32_e32 v82, 24, v78
	v_or_b32_e32 v83, 32, v78
	v_or_b32_e32 v84, 40, v78
	v_or_b32_e32 v85, 48, v78
	v_or_b32_e32 v86, 56, v78
	v_lshl_add_u64 v[18:19], s[18:19], 0, v[204:205]
	v_lshl_add_u64 v[24:25], s[4:5], 0, v[204:205]
	s_mov_b32 s3, s27
	s_branch .LBB0_38

.LBB0_233:
	s_and_b64 vcc, exec, s[10:11]
	s_cbranch_vccz .LBB0_402
	v_readlane_b32 s2, v209, 47
	v_readlane_b32 s3, v209, 48
	s_mov_b64 s[0:1], -1
	s_and_b64 vcc, exec, s[2:3]
	s_cbranch_vccz .LBB0_327
	v_readlane_b32 s0, v209, 49
	s_cmp_eq_u32 s0, 0
	s_cselect_b64 s[2:3], -1, 0
	s_cmp_lg_u32 s0, 0
	v_readlane_b32 s1, v209, 50
	s_cbranch_scc1 .LBB0_286
	v_readlane_b32 s0, v254, 10
	v_readlane_b32 s1, v254, 11
	s_andn2_b64 vcc, exec, s[0:1]
	s_cbranch_vccnz .LBB0_285
	v_readfirstlane_b32 s0, v234
	s_lshr_b32 s28, s0, 6
	v_readlane_b32 s0, v254, 15
	v_mov_b32_e32 v0, v234
	s_add_i32 s28, s28, s0
	v_readlane_b32 s4, v209, 30
	v_readfirstlane_b32 s0, v0
	s_lshr_b32 s0, s0, 6
	v_lshlrev_b32_e32 v1, 2, v0
	s_mulk_i32 s0, 0x4100
	v_bfe_u32 v9, v0, 4, 2
	v_and_b32_e32 v8, 60, v1
	s_add_i32 s0, s0, 0
	v_lshlrev_b32_e32 v1, 2, v8
	v_mul_u32_u24_e32 v2, 0x104, v9
	v_add3_u32 v11, s0, v1, v2
	v_and_b32_e32 v1, 7, v0
	v_bfe_u32 v78, v0, 3, 3
	v_lshlrev_b32_e32 v10, 3, v1
	v_mul_u32_u24_e32 v0, 0x820, v1
	v_lshlrev_b32_e32 v204, 4, v1
	v_lshlrev_b32_e32 v1, 2, v78
	v_add3_u32 v79, s0, v0, v1
	v_readlane_b32 s0, v209, 38
	v_readlane_b32 s1, v209, 39
	v_readlane_b32 s5, v209, 31
	v_or_b32_e32 v80, 8, v78
	v_lshl_add_u64 v[14:15], s[0:1], 0, v[204:205]
	v_readlane_b32 s0, v209, 32
	v_readlane_b32 s1, v209, 33
	v_lshl_add_u64 v[12:13], s[4:5], 0, v[204:205]
	v_or_b32_e32 v81, 16, v78
	v_lshl_add_u64 v[16:17], s[0:1], 0, v[204:205]
	v_readlane_b32 s0, v209, 36
	v_readlane_b32 s1, v209, 37
	v_or_b32_e32 v82, 24, v78
	v_or_b32_e32 v83, 32, v78
	v_lshl_add_u64 v[20:21], s[0:1], 0, v[204:205]
	v_readlane_b32 s0, v209, 34
	v_readlane_b32 s1, v209, 35
	v_or_b32_e32 v84, 40, v78
	v_or_b32_e32 v85, 48, v78
	v_lshl_add_u64 v[22:23], s[0:1], 0, v[204:205]
	v_readlane_b32 s0, v209, 40
	v_readlane_b32 s1, v209, 41
	v_or_b32_e32 v86, 56, v78
	v_lshl_add_u64 v[18:19], s[18:19], 0, v[204:205]
	v_lshl_add_u64 v[24:25], s[0:1], 0, v[204:205]
	s_mov_b32 s29, 0
	s_mov_b32 s8, 0x7d53
	s_mov_b32 s9, 0x0
	s_mov_b64 s[0:1], 19
	s_branch .LBB0_239
